# KIND0 diff-attention tile loop rotated by hand: PV of second softmax of tile j-1 under exps of first softmax of tile j, QK MFMAs carry pack/row-sum work
# speedup vs baseline: 1.0163x; 1.0083x over previous
; DI int otid() { int t = threadIdx.x; asm volatile("" : "+v"(t)); return t; }
; template <int KIND>
; DI void attn_unit(const Params& p, int l, int b, int head, int qt, int qcol, int kcol, int vfeat, int gcol, int mixcol,
;                   int t1, int n1, int t2, int n2, char* smem) {
;     const int tid = otid(), lane = tid & 63, wave = tid >> 6, r = lane & 31, h = lane >> 5;
;     const int tq = qt * 128 + 32 * wave + r;
;     const size_t qrow = (size_t)b * TPB + tq;
;     const bf16_t* kbase = p.qkv + ((size_t)(kcol >> 6) * NTOK + (size_t)b * TPB) * 64;
;     const bf16_t* vbase = p.vT + ((size_t)b * 12 + (vfeat >> 6)) * 36 * 4096;
;     const int nt = n1 + n2;
;     bf16x8 qf[4];
;     {
;         const bf16_t* qp = p.qkv + ((size_t)(qcol >> 6) * NTOK + qrow) * 64 + 8 * h;
; #pragma unroll
;         for (int s = 0; s < 4; ++s) qf[s] = *(const bf16x8*)(qp + 16 * s);
;     }
;     int nrow = 0, r0w = 0, qc = 0, c0 = 0;
;     if (KIND == 2) {
;         nrow = 2 * qt + (wave >> 1); r0w = min(max(nrow - 4, 0), 24);
;         qc = 32 * (wave & 1) + r; c0 = min(max(qc - 8, 0), 48);
;         float* bias = (float*)(smem + ATT_BIAS);
;         for (int i = tid; i < 15 * 32; i += NTHREADS) { const int rr = i >> 5, cc = i & 31; bias[i] = cc < 31 ? p.rpb[((size_t)l * 6 + head) * 465 + rr * 31 + cc] * LOG2E : -INFINITY; }
;     }
;     int bcol[2][16];
;     if (KIND == 2) {
; #pragma unroll
;         for (int t = 0; t < 2; ++t)
; #pragma unroll
;             for (int e = 0; e < 16; ++e) {
;                 const int kc = 32 * t + crow(e, h);
;                 bcol[t][e] = ((unsigned)(kc - c0) < 16u) ? (kc - qc + 15) * 4 : 31 * 4;
;             }
;     }
;     f32x16 O0[2], O1[2];
; #pragma unroll
;     for (int t = 0; t < 2; ++t)
; #pragma unroll
;         for (int e = 0; e < 16; ++e) { O0[t][e] = 0.f; O1[t][e] = 0.f; }
;     float l0 = 0.f, l1 = 0.f;
;     const float zb = p.lam[8 + l * 4 + ((KIND == 1 && qcol >= 2048) ? 3 : KIND)];
;     f32x16 cz;
; #pragma unroll
;     for (int e = 0; e < 16; ++e) cz[e] = -zb;
;     const int kvoff = (8 * wave + (lane >> 3)) * 64 + (((lane & 7) ^ (((wave & 1) << 2) | (lane >> 4))) << 3);
;     const int xr = (r >> 1) & 7;
;     __syncthreads();
;     KV_ISSUE(t1, 0);
;     if (nt > 1) KV_ISSUE((1 < n1) ? t1 + 1 : t2 + (1 - n1), 1);
;     int sc = 0, sn = 2;
.LBB0_81:
	s_and_b32 s6, s8, 3
	s_mul_i32 s8, s6, 0x4800
	s_lshl_b32 s7, s7, 7
	s_mul_i32 s29, s35, 0x900
	s_add_i32 s5, s8, 0x12000
	s_mul_hi_i32 s9, s35, 0x900
	s_add_u32 s56, s29, s5
	s_mul_i32 s34, s35, 12
	v_mov_b32_e32 v23, v200
	s_addc_u32 s57, s9, 0
	s_mul_hi_i32 s5, s35, 12
	s_or_b32 s34, s34, s6
	s_load_dwordx4 s[40:43], s[0:1], 0xc0
	s_load_dwordx2 s[50:51], s[0:1], 0xf8
	v_ashrrev_i32_e32 v16, 6, v23
	s_mul_i32 s53, s34, 0x48000
	s_mul_hi_u32 s34, s34, 0x48000
	s_mul_i32 s5, s5, 0x48000
	v_and_b32_e32 v22, 31, v23
	v_lshl_add_u32 v0, v16, 5, s7
	s_lshl_b64 s[56:57], s[56:57], 7
	s_add_i32 s5, s34, s5
	v_or_b32_e32 v0, v0, v22
	s_add_u32 s58, s29, s8
	v_ashrrev_i32_e32 v1, 31, v0
	s_addc_u32 s59, s9, 0
	v_lshl_add_u64 v[0:1], s[58:59], 0, v[0:1]
	s_waitcnt lgkmcnt(0)
	s_add_u32 s58, s40, s56
	v_bfe_u32 v214, v23, 5, 1
	v_lshlrev_b64 v[0:1], 7, v[0:1]
	s_addc_u32 s59, s41, s57
	s_lshl_b64 s[56:57], s[48:49], 2
	v_lshl_add_u64 v[0:1], s[40:41], 0, v[0:1]
	v_lshlrev_b32_e32 v192, 4, v214
	s_add_u32 s56, s50, s56
	v_lshl_add_u64 v[0:1], v[0:1], 0, v[192:193]
	s_addc_u32 s57, s51, s57
	global_load_dwordx4 v[152:155], v[0:1], off
	global_load_dwordx4 v[144:147], v[0:1], off offset:32
	global_load_dwordx4 v[156:159], v[0:1], off offset:64
	global_load_dwordx4 v[148:151], v[0:1], off offset:96
	v_lshlrev_b32_e32 v17, 9, v16
	global_load_dword v0, v193, s[56:57] offset:32
	v_lshlrev_b32_e32 v18, 3, v23
	s_movk_i32 s56, 0x1c0
	v_lshlrev_b32_e32 v16, 2, v16
	v_and_or_b32 v17, v18, s56, v17
	v_and_b32_e32 v18, 7, v23
	v_and_b32_e32 v16, 4, v16
	v_bfe_u32 v19, v23, 4, 2
	s_add_u32 s53, s42, s53
	v_bitop3_b32 v16, v16, v18, v19 bitop3:0x36
	s_addc_u32 s5, s43, s5
	v_lshl_or_b32 v16, v16, 3, v17
	s_lshl_b32 s4, s4, 13
	s_add_u32 s56, s58, s4
	v_ashrrev_i32_e32 v17, 31, v16
	s_addc_u32 s57, s59, 0
	v_lshlrev_b64 v[16:17], 1, v[16:17]
	v_lshl_add_u64 v[20:21], s[56:57], 0, v[16:17]
	s_add_u32 s56, s53, s4
	v_lshl_add_u32 v220, v23, 4, 32
	v_lshrrev_b32_e32 v28, 1, v23
	v_bfe_u32 v29, v23, 1, 3
	s_addc_u32 s57, s5, 0
	v_readfirstlane_b32 s5, v220
	v_add_u32_e32 v23, 0x1000, v220
	s_mov_b32 m0, s5
	v_readfirstlane_b32 s5, v23
	v_add_u32_e32 v23, 0x2000, v220
	s_barrier
	global_load_lds_dwordx4 v[20:21], off
	v_lshl_add_u64 v[24:25], v[20:21], 0, s[26:27]
	s_mov_b32 m0, s5
	v_readfirstlane_b32 s5, v23
	v_add_u32_e32 v23, 0x3000, v220
	v_lshl_add_u64 v[18:19], s[56:57], 0, v[16:17]
	global_load_lds_dwordx4 v[24:25], off
	s_mov_b32 m0, s5
	v_readfirstlane_b32 s5, v23
	v_add_u32_e32 v23, 0x4000, v220
	global_load_lds_dwordx4 v[18:19], off
	v_lshl_add_u64 v[24:25], v[18:19], 0, s[26:27]
	s_mov_b32 m0, s5
	v_readfirstlane_b32 s5, v23
	v_add_u32_e32 v23, 0x5000, v220
	global_load_lds_dwordx4 v[24:25], off
	v_lshl_add_u64 v[24:25], v[20:21], 0, s[16:17]
	s_mov_b32 m0, s5
	v_readfirstlane_b32 s5, v23
	global_load_lds_dwordx4 v[24:25], off
	v_lshl_add_u64 v[20:21], v[20:21], 0, s[90:91]
	s_mov_b32 m0, s5
	v_lshl_add_u64 v[26:27], v[18:19], 0, s[16:17]
	global_load_lds_dwordx4 v[20:21], off
	v_add_u32_e32 v20, 0x6000, v220
	v_lshl_add_u64 v[18:19], v[18:19], 0, s[90:91]
	v_readfirstlane_b32 s5, v20
	v_add_u32_e32 v20, 0x7000, v220
	s_mov_b32 m0, s5
	v_readfirstlane_b32 s5, v20
	global_load_lds_dwordx4 v[26:27], off
	s_mov_b32 m0, s5
	s_lshl_b32 s5, s52, 13
	global_load_lds_dwordx4 v[18:19], off
	s_add_u32 s52, s5, 0x2000
	s_mul_i32 s53, s35, 0x360000
	s_mul_i32 s56, s6, 0x48000
	s_mul_hi_i32 s5, s35, 0x360000
	s_add_u32 s53, s53, s56
	s_addc_u32 s5, s5, 0
	s_add_u32 s53, s53, s4
	s_addc_u32 s5, s5, 0
	s_add_u32 s42, s42, s53
	s_addc_u32 s43, s43, s5
	v_lshl_add_u64 v[196:197], s[42:43], 0, v[16:17]
	s_mul_i32 s5, s6, 0x240000
	s_mul_hi_i32 s42, s35, 0x48000
	s_mul_i32 s35, s35, 0x48000
	s_add_u32 s5, s5, s35
	s_addc_u32 s35, 0, s42
	s_add_u32 s4, s5, s4
	v_bitop3_b32 v18, v214, v28, 7 bitop3:0x78
	s_addc_u32 s5, s35, 0
	v_lshlrev_b32_e32 v219, 4, v18
	v_bitop3_b32 v18, v214, v29, 2 bitop3:0x36
	s_add_u32 s4, s40, s4
	v_lshlrev_b32_e32 v218, 4, v18
	v_bitop3_b32 v18, v214, v29, 4 bitop3:0x36
	s_addc_u32 s5, s41, s5
	s_waitcnt vmcnt(0)
	v_xor_b32_e32 v0, 0x80000000, v0
	v_lshlrev_b32_e32 v217, 7, v22
	v_lshlrev_b32_e32 v216, 4, v18
	v_bitop3_b32 v18, v214, v29, 6 bitop3:0x36
	v_lshl_add_u64 v[198:199], s[4:5], 0, v[16:17]
	v_mov_b32_e32 v16, 0
	s_mov_b32 s34, 2
	v_mov_b32_e32 v1, v0
	v_mov_b32_e32 v2, v0
	v_mov_b32_e32 v3, v0
	v_mov_b32_e32 v4, v0
	v_mov_b32_e32 v5, v0
	v_mov_b32_e32 v6, v0
	v_mov_b32_e32 v7, v0
	v_mov_b32_e32 v8, v0
	v_mov_b32_e32 v9, v0
	v_mov_b32_e32 v10, v0
	v_mov_b32_e32 v11, v0
	v_mov_b32_e32 v12, v0
	v_mov_b32_e32 v13, v0
	v_mov_b32_e32 v14, v0
	v_mov_b32_e32 v15, v0
	v_lshlrev_b32_e32 v215, 4, v18
	v_add_u32_e32 v221, 32, v217
	s_mov_b32 s35, 0
	s_mov_b64 s[4:5], 0
	v_mov_b32_e32 v17, v16
	v_mov_b32_e32 v18, v16
	v_mov_b32_e32 v19, v16
	v_mov_b32_e32 v20, v16
	v_mov_b32_e32 v21, v16
	v_mov_b32_e32 v22, v16
	v_mov_b32_e32 v23, v16
	v_mov_b32_e32 v24, v16
	v_mov_b32_e32 v25, v16
	v_mov_b32_e32 v26, v16
	v_mov_b32_e32 v27, v16
	v_mov_b32_e32 v28, v16
	v_mov_b32_e32 v29, v16
	v_mov_b32_e32 v30, v16
	v_mov_b32_e32 v31, v16
	v_mov_b32_e32 v48, v16
	v_mov_b32_e32 v49, v16
	v_mov_b32_e32 v50, v16
	v_mov_b32_e32 v51, v16
	v_mov_b32_e32 v52, v16
	v_mov_b32_e32 v53, v16
	v_mov_b32_e32 v54, v16
	v_mov_b32_e32 v55, v16
	v_mov_b32_e32 v56, v16
	v_mov_b32_e32 v57, v16
	v_mov_b32_e32 v58, v16
	v_mov_b32_e32 v59, v16
	v_mov_b32_e32 v60, v16
	v_mov_b32_e32 v61, v16
	v_mov_b32_e32 v62, v16
	v_mov_b32_e32 v63, v16
	v_mov_b32_e32 v32, v16
	v_mov_b32_e32 v33, v16
	v_mov_b32_e32 v34, v16
	v_mov_b32_e32 v35, v16
	v_mov_b32_e32 v36, v16
	v_mov_b32_e32 v37, v16
; DI void softmax_tile(f32x16 (&S)[2], float& lsum) {
;     f2_t ps = {0.f, 0.f};
; #pragma unroll
;     for (int t = 0; t < 2; ++t)
; #pragma unroll
;         for (int e = 0; e < 16; e += 2) {
;             f2_t pv; pv.x = __builtin_amdgcn_exp2f(S[t][e]); pv.y = __builtin_amdgcn_exp2f(S[t][e + 1]);
;             S[t][e] = pv.x; S[t][e + 1] = pv.y;
;             ps += pv;
;         }
;     lsum += ps.x + ps.y;
; }
; DI void pv_tile(const f32x16 (&S)[2], f32x16 (&O)[2], const bf16x8 (&vf)[8]) {
; #pragma unroll
;     for (int s = 0; s < 4; ++s) {
;         const bf16x8 pf = pack8(S[s >> 1], s & 1);
; template <int KIND>
; DI void attn_unit(const Params& p, int l, int b, int head, int qt, int qcol, int kcol, int vfeat, int gcol, int mixcol,
;                   int t1, int n1, int t2, int n2, char* smem) {
;     ...
;     for (int it = 0; it < nt; ++it) {
;         const int tile = (it < n1) ? t1 + it : t2 + (it - n1);
;         if (it + 1 < nt) asm volatile("s_waitcnt vmcnt(4)" ::: "memory"); else asm volatile("s_waitcnt vmcnt(0)" ::: "memory");
;         __builtin_amdgcn_s_barrier();
;         const char* sk = smem + sc * ATT_SLOT;
;         const char* sv = sk + ATT_V;
;         bool active = true;
;         if (KIND == 2 && tile < 32) active = (tile >= r0w) && (tile < r0w + 8);
;         bf16x8 kf[8], vf[8];
;         if (active) {
; #pragma unroll
;             for (int s = 0; s < 4; ++s)
; #pragma unroll
;                 for (int t = 0; t < 2; ++t) kf[2 * s + t] = *(const bf16x8*)(sk + (32 * t + r) * 128 + (((2 * s + h) ^ xr) << 4));
;         }
;         __builtin_amdgcn_sched_barrier(0);
;         if (it + 2 < nt) { const int nx = (it + 2 < n1) ? t1 + it + 2 : t2 + (it + 2 - n1); KV_ISSUE(nx, sn); }
;         sc = (sc == 2) ? 0 : sc + 1; sn = (sn == 2) ? 0 : sn + 1;
;         __builtin_amdgcn_sched_barrier(0);
;         if (active) {
;     ...
;             if (KIND == 0) {
;                 f32x16 S0[2], S1[2];
; #pragma unroll
;                 for (int t = 0; t < 2; ++t) { S0[t] = MFMA(kf[t], qf[0], cz); S1[t] = MFMA(kf[4 + t], qf[2], cz); }
; #pragma unroll
;                 for (int t = 0; t < 2; ++t) { S0[t] = MFMA(kf[2 + t], qf[1], S0[t]); S1[t] = MFMA(kf[6 + t], qf[3], S1[t]); }
;                 LOAD_VF();
;                 softmax_tile(S0, l0);
;                 pv_tile(S0, O0, vf);
;                 softmax_tile(S1, l1);
;                 pv_tile(S1, O1, vf);
	v_mov_b32_e32 v38, v16
	v_mov_b32_e32 v39, v16
	v_mov_b32_e32 v40, v16
	v_mov_b32_e32 v41, v16
	v_mov_b32_e32 v42, v16
	v_mov_b32_e32 v43, v16
	v_mov_b32_e32 v44, v16
	v_mov_b32_e32 v45, v16
	v_mov_b32_e32 v46, v16
	v_mov_b32_e32 v47, v16
	v_mov_b32_e32 v64, v16
	v_mov_b32_e32 v65, v16
	v_mov_b32_e32 v66, v16
	v_mov_b32_e32 v67, v16
	v_mov_b32_e32 v68, v16
	v_mov_b32_e32 v69, v16
	v_mov_b32_e32 v70, v16
	v_mov_b32_e32 v71, v16
	v_mov_b32_e32 v72, v16
	v_mov_b32_e32 v73, v16
	v_mov_b32_e32 v74, v16
	v_mov_b32_e32 v75, v16
	v_mov_b32_e32 v76, v16
	v_mov_b32_e32 v77, v16
	v_mov_b32_e32 v78, v16
	v_mov_b32_e32 v79, v16
	v_mov_b32_e32 v194, v16
	v_mov_b32_e32 v195, v16
	v_readfirstlane_b32 s100, v220
	v_mov_b32_e32 v80, 0
	v_mov_b32_e32 v81, 0
	v_mov_b32_e32 v82, 0
	v_mov_b32_e32 v83, 0
	v_mov_b32_e32 v84, 0
	v_mov_b32_e32 v85, 0
	v_mov_b32_e32 v86, 0
	v_mov_b32_e32 v87, 0
	v_mov_b32_e32 v88, 0
	v_mov_b32_e32 v89, 0
	v_mov_b32_e32 v90, 0
	v_mov_b32_e32 v91, 0
	v_mov_b32_e32 v92, 0
	v_mov_b32_e32 v93, 0
	v_mov_b32_e32 v94, 0
	v_mov_b32_e32 v95, 0
	v_mov_b32_e32 v96, 0
	v_mov_b32_e32 v97, 0
	v_mov_b32_e32 v98, 0
	v_mov_b32_e32 v99, 0
	v_mov_b32_e32 v100, 0
	v_mov_b32_e32 v101, 0
	v_mov_b32_e32 v102, 0
	v_mov_b32_e32 v103, 0
	v_mov_b32_e32 v104, 0
	v_mov_b32_e32 v105, 0
	v_mov_b32_e32 v106, 0
	v_mov_b32_e32 v107, 0
	v_mov_b32_e32 v108, 0
	v_mov_b32_e32 v109, 0
	v_mov_b32_e32 v110, 0
	v_mov_b32_e32 v111, 0
	v_mov_b32_e32 v160, 0
	v_mov_b32_e32 v161, 0
	v_mov_b32_e32 v162, 0
	v_mov_b32_e32 v163, 0
	v_mov_b32_e32 v164, 0
	v_mov_b32_e32 v165, 0
	v_mov_b32_e32 v166, 0
	v_mov_b32_e32 v167, 0
	v_mov_b32_e32 v168, 0
	v_mov_b32_e32 v169, 0
	v_mov_b32_e32 v170, 0
	v_mov_b32_e32 v171, 0
	v_mov_b32_e32 v172, 0
	v_mov_b32_e32 v173, 0
	v_mov_b32_e32 v174, 0
	v_mov_b32_e32 v175, 0
	v_mov_b32_e32 v176, 0
	v_mov_b32_e32 v177, 0
	v_mov_b32_e32 v178, 0
	v_mov_b32_e32 v179, 0
	v_mov_b32_e32 v180, 0
	v_mov_b32_e32 v181, 0
	v_mov_b32_e32 v182, 0
	v_mov_b32_e32 v183, 0
	v_mov_b32_e32 v184, 0
	v_mov_b32_e32 v185, 0
	v_mov_b32_e32 v186, 0
	v_mov_b32_e32 v187, 0
	v_mov_b32_e32 v188, 0
	v_mov_b32_e32 v189, 0
	v_mov_b32_e32 v190, 0
	v_mov_b32_e32 v191, 0
	v_mov_b32_e32 v252, 0
	v_mov_b32_e32 v253, 0
.LBB0_82:
	v_lshl_add_u32 v225, s35, 14, v221
	v_add_u32_e32 v222, v225, v218
	v_add_u32_e32 v223, v225, v216
	v_add_u32_e32 v224, v225, v215
	v_add_u32_e32 v225, v225, v219
	s_waitcnt vmcnt(4)
	s_barrier
	ds_read_b128 v[234:237], v225
	ds_read_b128 v[238:241], v225 offset:4096
	ds_read_b128 v[242:245], v222
	ds_read_b128 v[246:249], v222 offset:4096
	v_lshl_add_u64 v[226:227], v[198:199], 0, s[4:5]
	s_mov_b64 s[42:43], 0x904000
	v_lshl_add_u64 v[228:229], v[226:227], 0, s[42:43]
	s_mov_b64 s[42:43], 0x905000
	v_lshl_add_u64 v[226:227], v[226:227], 0, s[42:43]
	v_lshl_add_u64 v[230:231], v[196:197], 0, s[4:5]
	v_lshl_add_u64 v[232:233], v[230:231], 0, s[92:93]
	v_lshl_add_u64 v[230:231], v[230:231], 0, s[94:95]
	s_lshl_b32 s101, s34, 14
	s_add_i32 s101, s101, s100
	s_add_i32 s42, s35, 1
	s_cmp_lg_u32 s35, 2
	s_cselect_b32 s35, s42, 0
	s_add_i32 s42, s34, 1
	v_add_f32_e32 v252, v80, v252
	v_add_f32_e32 v253, v81, v253
	v_cvt_pk_bf16_f32 v80, v80, v81
	v_add_f32_e32 v252, v82, v252
	v_add_f32_e32 v253, v83, v253
	v_cvt_pk_bf16_f32 v81, v82, v83
	v_add_f32_e32 v252, v84, v252
	v_add_f32_e32 v253, v85, v253
	v_cvt_pk_bf16_f32 v82, v84, v85
	v_add_f32_e32 v252, v86, v252
	v_add_f32_e32 v253, v87, v253
	v_cvt_pk_bf16_f32 v83, v86, v87
	s_mov_b32 m0, s101
	s_waitcnt lgkmcnt(0)
	v_mfma_f32_32x32x16_bf16 v[128:143], v[234:237], v[152:155], v[0:15]
	global_load_lds_dwordx4 v[228:229], off
	s_add_u32 m0, s101, 0x1000
	v_add_f32_e32 v252, v88, v252
	v_add_f32_e32 v253, v89, v253
	v_cvt_pk_bf16_f32 v88, v88, v89
	v_mfma_f32_32x32x16_bf16 v[112:127], v[238:241], v[152:155], v[0:15]
	global_load_lds_dwordx4 v[226:227], off
	s_add_u32 m0, s101, 0x2000
	v_add_f32_e32 v252, v90, v252
	v_add_f32_e32 v253, v91, v253
	v_cvt_pk_bf16_f32 v89, v90, v91
	v_mfma_f32_32x32x16_bf16 v[128:143], v[242:245], v[144:147], v[128:143]
	global_load_lds_dwordx4 v[232:233], off
	s_add_u32 m0, s101, 0x3000
	v_add_f32_e32 v252, v92, v252
	v_add_f32_e32 v253, v93, v253
	v_cvt_pk_bf16_f32 v90, v92, v93
	v_mfma_f32_32x32x16_bf16 v[112:127], v[246:249], v[144:147], v[112:127]
	global_load_lds_dwordx4 v[230:231], off
	v_add_f32_e32 v252, v94, v252
	v_add_f32_e32 v253, v95, v253
	v_cvt_pk_bf16_f32 v91, v94, v95
	v_add_f32_e32 v252, v252, v253
	v_add_f32_e32 v194, v194, v252
	s_cmp_lg_u32 s34, 2
	s_cselect_b32 s34, s42, 0
	ds_read_b128 v[234:237], v223
	ds_read_b128 v[238:241], v223 offset:4096
	ds_read_b128 v[242:245], v224
	ds_read_b128 v[246:249], v224 offset:4096
	v_mfma_f32_32x32x16_bf16 v[64:79], v[188:191], v[96:99], v[64:79]
	v_exp_f32_e32 v128, v128
	v_exp_f32_e32 v129, v129
	v_exp_f32_e32 v130, v130
	v_exp_f32_e32 v131, v131
	v_mfma_f32_32x32x16_bf16 v[16:31], v[184:187], v[96:99], v[16:31]
	v_exp_f32_e32 v132, v132
	v_exp_f32_e32 v133, v133
	v_exp_f32_e32 v134, v134
	v_exp_f32_e32 v135, v135
	v_mfma_f32_32x32x16_bf16 v[64:79], v[180:183], v[104:107], v[64:79]
	v_exp_f32_e32 v136, v136
	v_exp_f32_e32 v137, v137
	v_exp_f32_e32 v138, v138
	v_exp_f32_e32 v139, v139
	v_add_f32_e64 v250, v128, 0
	v_add_f32_e64 v251, v129, 0
	v_cvt_pk_bf16_f32 v128, v128, v129
	v_add_f32_e32 v250, v130, v250
	v_add_f32_e32 v251, v131, v251
	v_cvt_pk_bf16_f32 v129, v130, v131
	v_mfma_f32_32x32x16_bf16 v[16:31], v[176:179], v[104:107], v[16:31]
	v_exp_f32_e32 v140, v140
	v_exp_f32_e32 v141, v141
	v_exp_f32_e32 v142, v142
	v_exp_f32_e32 v143, v143
	v_add_f32_e32 v250, v132, v250
	v_add_f32_e32 v251, v133, v251
	v_cvt_pk_bf16_f32 v130, v132, v133
	v_add_f32_e32 v250, v134, v250
	v_add_f32_e32 v251, v135, v251
	v_cvt_pk_bf16_f32 v131, v134, v135
	v_mfma_f32_32x32x16_bf16 v[64:79], v[172:175], v[80:83], v[64:79]
	v_exp_f32_e32 v112, v112
	v_exp_f32_e32 v113, v113
	v_exp_f32_e32 v114, v114
	v_exp_f32_e32 v115, v115
	v_add_f32_e32 v250, v136, v250
	v_add_f32_e32 v251, v137, v251
	v_cvt_pk_bf16_f32 v136, v136, v137
	v_add_f32_e32 v250, v138, v250
	v_add_f32_e32 v251, v139, v251
	v_cvt_pk_bf16_f32 v137, v138, v139
	v_mfma_f32_32x32x16_bf16 v[16:31], v[168:171], v[80:83], v[16:31]
	v_exp_f32_e32 v116, v116
	v_exp_f32_e32 v117, v117
	v_exp_f32_e32 v118, v118
	v_exp_f32_e32 v119, v119
	v_add_f32_e32 v250, v140, v250
	v_add_f32_e32 v251, v141, v251
	v_cvt_pk_bf16_f32 v138, v140, v141
	v_add_f32_e32 v250, v142, v250
	v_add_f32_e32 v251, v143, v251
	v_cvt_pk_bf16_f32 v139, v142, v143
	v_mfma_f32_32x32x16_bf16 v[64:79], v[164:167], v[88:91], v[64:79]
	v_exp_f32_e32 v120, v120
	v_exp_f32_e32 v121, v121
	v_exp_f32_e32 v122, v122
	v_exp_f32_e32 v123, v123
	v_mfma_f32_32x32x16_bf16 v[16:31], v[160:163], v[88:91], v[16:31]
	v_exp_f32_e32 v124, v124
	v_exp_f32_e32 v125, v125
	v_exp_f32_e32 v126, v126
	v_exp_f32_e32 v127, v127
	s_waitcnt lgkmcnt(0)
; DI void softmax_tile(f32x16 (&S)[2], float& lsum) {
;     f2_t ps = {0.f, 0.f};
; #pragma unroll
;     for (int t = 0; t < 2; ++t)
; #pragma unroll
;         for (int e = 0; e < 16; e += 2) {
;             f2_t pv; pv.x = __builtin_amdgcn_exp2f(S[t][e]); pv.y = __builtin_amdgcn_exp2f(S[t][e + 1]);
;             S[t][e] = pv.x; S[t][e + 1] = pv.y;
;             ps += pv;
;         }
;     lsum += ps.x + ps.y;
; }
; DI void pv_tile(const f32x16 (&S)[2], f32x16 (&O)[2], const bf16x8 (&vf)[8]) {
; #pragma unroll
;     for (int s = 0; s < 4; ++s) {
;         const bf16x8 pf = pack8(S[s >> 1], s & 1);
; template <int KIND>
; DI void attn_unit(const Params& p, int l, int b, int head, int qt, int qcol, int kcol, int vfeat, int gcol, int mixcol,
;                   int t1, int n1, int t2, int n2, char* smem) {
;     ...
;     for (int it = 0; it < nt; ++it) {
;         const int tile = (it < n1) ? t1 + it : t2 + (it - n1);
;         if (it + 1 < nt) asm volatile("s_waitcnt vmcnt(4)" ::: "memory"); else asm volatile("s_waitcnt vmcnt(0)" ::: "memory");
;         __builtin_amdgcn_s_barrier();
;         const char* sk = smem + sc * ATT_SLOT;
;         const char* sv = sk + ATT_V;
;         bool active = true;
;         if (KIND == 2 && tile < 32) active = (tile >= r0w) && (tile < r0w + 8);
;         bf16x8 kf[8], vf[8];
;         if (active) {
; #pragma unroll
;             for (int s = 0; s < 4; ++s)
; #pragma unroll
;                 for (int t = 0; t < 2; ++t) kf[2 * s + t] = *(const bf16x8*)(sk + (32 * t + r) * 128 + (((2 * s + h) ^ xr) << 4));
;         }
;         __builtin_amdgcn_sched_barrier(0);
;         if (it + 2 < nt) { const int nx = (it + 2 < n1) ? t1 + it + 2 : t2 + (it + 2 - n1); KV_ISSUE(nx, sn); }
;         sc = (sc == 2) ? 0 : sc + 1; sn = (sn == 2) ? 0 : sn + 1;
;         __builtin_amdgcn_sched_barrier(0);
;         if (active) {
;     ...
;             if (KIND == 0) {
;                 f32x16 S0[2], S1[2];
; #pragma unroll
;                 for (int t = 0; t < 2; ++t) { S0[t] = MFMA(kf[t], qf[0], cz); S1[t] = MFMA(kf[4 + t], qf[2], cz); }
; #pragma unroll
;                 for (int t = 0; t < 2; ++t) { S0[t] = MFMA(kf[2 + t], qf[1], S0[t]); S1[t] = MFMA(kf[6 + t], qf[3], S1[t]); }
;                 LOAD_VF();
;                 softmax_tile(S0, l0);
;                 pv_tile(S0, O0, vf);
;                 softmax_tile(S1, l1);
;                 pv_tile(S1, O1, vf);
	ds_read_b128 v[188:191], v225 offset:8192
	ds_read_b128 v[184:187], v225 offset:12288
	ds_read_b128 v[180:183], v222 offset:8192
	ds_read_b128 v[176:179], v222 offset:12288
	ds_read_b128 v[172:175], v223 offset:8192
	ds_read_b128 v[168:171], v223 offset:12288
	ds_read_b128 v[164:167], v224 offset:8192
	ds_read_b128 v[160:163], v224 offset:12288
	v_mfma_f32_32x32x16_bf16 v[96:111], v[234:237], v[156:159], v[0:15]
	v_add_f32_e32 v250, v112, v250
	v_add_f32_e32 v251, v113, v251
	v_cvt_pk_bf16_f32 v112, v112, v113
	v_add_f32_e32 v250, v114, v250
	v_add_f32_e32 v251, v115, v251
	v_cvt_pk_bf16_f32 v113, v114, v115
	v_mfma_f32_32x32x16_bf16 v[80:95], v[238:241], v[156:159], v[0:15]
	v_add_f32_e32 v250, v116, v250
	v_add_f32_e32 v251, v117, v251
	v_cvt_pk_bf16_f32 v114, v116, v117
	v_add_f32_e32 v250, v118, v250
	v_add_f32_e32 v251, v119, v251
	v_cvt_pk_bf16_f32 v115, v118, v119
	v_mfma_f32_32x32x16_bf16 v[96:111], v[242:245], v[148:151], v[96:111]
	v_add_f32_e32 v250, v120, v250
	v_add_f32_e32 v251, v121, v251
	v_cvt_pk_bf16_f32 v120, v120, v121
	v_add_f32_e32 v250, v122, v250
	v_add_f32_e32 v251, v123, v251
	v_cvt_pk_bf16_f32 v121, v122, v123
	v_mfma_f32_32x32x16_bf16 v[80:95], v[246:249], v[148:151], v[80:95]
	v_add_f32_e32 v250, v124, v250
	v_add_f32_e32 v251, v125, v251
	v_cvt_pk_bf16_f32 v122, v124, v125
	v_add_f32_e32 v250, v126, v250
	v_add_f32_e32 v251, v127, v251
	v_cvt_pk_bf16_f32 v123, v126, v127
	v_add_f32_e32 v250, v250, v251
	v_add_f32_e32 v195, v195, v250
	s_add_u32 s4, s4, 0x2000
	s_addc_u32 s5, s5, 0
	s_waitcnt lgkmcnt(0)
	v_mfma_f32_32x32x16_bf16 v[48:63], v[188:191], v[128:131], v[48:63]
	v_exp_f32_e32 v96, v96
	v_exp_f32_e32 v97, v97
	v_exp_f32_e32 v98, v98
	v_exp_f32_e32 v99, v99
	v_mfma_f32_32x32x16_bf16 v[32:47], v[184:187], v[128:131], v[32:47]
	v_exp_f32_e32 v100, v100
	v_exp_f32_e32 v101, v101
	v_exp_f32_e32 v102, v102
	v_exp_f32_e32 v103, v103
	v_mfma_f32_32x32x16_bf16 v[48:63], v[180:183], v[136:139], v[48:63]
	v_exp_f32_e32 v104, v104
	v_exp_f32_e32 v105, v105
	v_exp_f32_e32 v106, v106
	v_exp_f32_e32 v107, v107
	v_add_f32_e64 v252, v96, 0
	v_add_f32_e64 v253, v97, 0
	v_cvt_pk_bf16_f32 v96, v96, v97
	v_add_f32_e32 v252, v98, v252
	v_add_f32_e32 v253, v99, v253
	v_cvt_pk_bf16_f32 v97, v98, v99
	v_mfma_f32_32x32x16_bf16 v[32:47], v[176:179], v[136:139], v[32:47]
	v_exp_f32_e32 v108, v108
	v_exp_f32_e32 v109, v109
	v_exp_f32_e32 v110, v110
	v_exp_f32_e32 v111, v111
	v_add_f32_e32 v252, v100, v252
	v_add_f32_e32 v253, v101, v253
	v_cvt_pk_bf16_f32 v98, v100, v101
	v_add_f32_e32 v252, v102, v252
	v_add_f32_e32 v253, v103, v253
	v_cvt_pk_bf16_f32 v99, v102, v103
	v_mfma_f32_32x32x16_bf16 v[48:63], v[172:175], v[112:115], v[48:63]
	v_exp_f32_e32 v80, v80
	v_exp_f32_e32 v81, v81
	v_exp_f32_e32 v82, v82
	v_exp_f32_e32 v83, v83
	v_add_f32_e32 v252, v104, v252
	v_add_f32_e32 v253, v105, v253
	v_cvt_pk_bf16_f32 v104, v104, v105
	v_add_f32_e32 v252, v106, v252
	v_add_f32_e32 v253, v107, v253
	v_cvt_pk_bf16_f32 v105, v106, v107
	v_mfma_f32_32x32x16_bf16 v[32:47], v[168:171], v[112:115], v[32:47]
	v_exp_f32_e32 v84, v84
	v_exp_f32_e32 v85, v85
	v_exp_f32_e32 v86, v86
	v_exp_f32_e32 v87, v87
	v_add_f32_e32 v252, v108, v252
	v_add_f32_e32 v253, v109, v253
	v_cvt_pk_bf16_f32 v106, v108, v109
	v_add_f32_e32 v252, v110, v252
	v_add_f32_e32 v253, v111, v253
	v_cvt_pk_bf16_f32 v107, v110, v111
	v_mfma_f32_32x32x16_bf16 v[48:63], v[164:167], v[120:123], v[48:63]
	v_exp_f32_e32 v88, v88
	v_exp_f32_e32 v89, v89
	v_exp_f32_e32 v90, v90
	v_exp_f32_e32 v91, v91
	v_mfma_f32_32x32x16_bf16 v[32:47], v[160:163], v[120:123], v[32:47]
	v_exp_f32_e32 v92, v92
	v_exp_f32_e32 v93, v93
	v_exp_f32_e32 v94, v94
	v_exp_f32_e32 v95, v95
	s_cmp_eq_u32 s52, s4
	s_cbranch_scc0 .LBB0_82
	v_add_f32_e32 v252, v80, v252
	v_add_f32_e32 v253, v81, v253
	v_cvt_pk_bf16_f32 v80, v80, v81
	v_add_f32_e32 v252, v82, v252
	v_add_f32_e32 v253, v83, v253
	v_cvt_pk_bf16_f32 v81, v82, v83
	v_add_f32_e32 v252, v84, v252
	v_add_f32_e32 v253, v85, v253
	v_cvt_pk_bf16_f32 v82, v84, v85
	v_add_f32_e32 v252, v86, v252
	v_add_f32_e32 v253, v87, v253
	v_cvt_pk_bf16_f32 v83, v86, v87
	v_add_f32_e32 v252, v88, v252
	v_add_f32_e32 v253, v89, v253
	v_cvt_pk_bf16_f32 v88, v88, v89
	v_add_f32_e32 v252, v90, v252
	v_add_f32_e32 v253, v91, v253
	v_cvt_pk_bf16_f32 v89, v90, v91
	v_add_f32_e32 v252, v92, v252
	v_add_f32_e32 v253, v93, v253
	v_cvt_pk_bf16_f32 v90, v92, v93
	v_add_f32_e32 v252, v94, v252
	v_add_f32_e32 v253, v95, v253
	v_cvt_pk_bf16_f32 v91, v94, v95
	v_add_f32_e32 v252, v252, v253
	v_add_f32_e32 v194, v194, v252
	v_mfma_f32_32x32x16_bf16 v[64:79], v[188:191], v[96:99], v[64:79]
	v_mfma_f32_32x32x16_bf16 v[16:31], v[184:187], v[96:99], v[16:31]
	v_mfma_f32_32x32x16_bf16 v[64:79], v[180:183], v[104:107], v[64:79]
	v_mfma_f32_32x32x16_bf16 v[16:31], v[176:179], v[104:107], v[16:31]
	v_mfma_f32_32x32x16_bf16 v[64:79], v[172:175], v[80:83], v[64:79]
	v_mfma_f32_32x32x16_bf16 v[16:31], v[168:171], v[80:83], v[16:31]
	v_mfma_f32_32x32x16_bf16 v[64:79], v[164:167], v[88:91], v[64:79]
	v_mfma_f32_32x32x16_bf16 v[16:31], v[160:163], v[88:91], v[16:31]
	s_lshl_b32 s4, s35, 14
	s_add_i32 s5, s4, 32
	v_add_u32_e32 v92, s5, v217
	v_add_u32_e32 v180, v92, v219
	v_add_u32_e32 v196, v92, v218
	v_add_u32_e32 v197, v92, v216
	v_add_u32_e32 v198, v92, v215
	s_waitcnt vmcnt(4)
	s_barrier
; #define MFMA(a, b, c) __builtin_amdgcn_mfma_f32_32x32x16_bf16((a), (b), (c), 0, 0, 0)
; #define KV_ISSUE(tile_, slot_) do { \
;     const bf16_t* kp_ = kbase + (size_t)(tile_) * 4096 + kvoff; const bf16_t* vp_ = vbase + (size_t)(tile_) * 4096 + kvoff; \
;     char* lp_ = smem + (slot_) * ATT_SLOT + tid * 16; \
;     dma16(kp_, lp_); dma16(kp_ + 2048, lp_ + 4096); dma16(vp_, lp_ + ATT_V); dma16(vp_ + 2048, lp_ + ATT_V + 4096); } while (0)
; template <int KIND>
; DI void attn_unit(const Params& p, int l, int b, int head, int qt, int qcol, int kcol, int vfeat, int gcol, int mixcol,
;                   int t1, int n1, int t2, int n2, char* smem) {
;     ...
;     for (int it = 0; it < nt; ++it) {
;         const int tile = (it < n1) ? t1 + it : t2 + (it - n1);
;         if (it + 1 < nt) asm volatile("s_waitcnt vmcnt(4)" ::: "memory"); else asm volatile("s_waitcnt vmcnt(0)" ::: "memory");
;         __builtin_amdgcn_s_barrier();
;         const char* sk = smem + sc * ATT_SLOT;
;         const char* sv = sk + ATT_V;
;         bool active = true;
;         if (KIND == 2 && tile < 32) active = (tile >= r0w) && (tile < r0w + 8);
;         bf16x8 kf[8], vf[8];
;         if (active) {
; #pragma unroll
;             for (int s = 0; s < 4; ++s)
; #pragma unroll
;                 for (int t = 0; t < 2; ++t) kf[2 * s + t] = *(const bf16x8*)(sk + (32 * t + r) * 128 + (((2 * s + h) ^ xr) << 4));
;         }
;         __builtin_amdgcn_sched_barrier(0);
;         if (it + 2 < nt) { const int nx = (it + 2 < n1) ? t1 + it + 2 : t2 + (it + 2 - n1); KV_ISSUE(nx, sn); }
;         sc = (sc == 2) ? 0 : sc + 1; sn = (sn == 2) ? 0 : sn + 1;
;         __builtin_amdgcn_sched_barrier(0);
;         if (active) {
;     ...
;             if (KIND == 0) {
;                 f32x16 S0[2], S1[2];
; #pragma unroll
;                 for (int t = 0; t < 2; ++t) { S0[t] = MFMA(kf[t], qf[0], cz); S1[t] = MFMA(kf[4 + t], qf[2], cz); }
; #pragma unroll
;                 for (int t = 0; t < 2; ++t) { S0[t] = MFMA(kf[2 + t], qf[1], S0[t]); S1[t] = MFMA(kf[6 + t], qf[3], S1[t]); }
;                 LOAD_VF();
;                 softmax_tile(S0, l0);
;                 pv_tile(S0, O0, vf);
;                 softmax_tile(S1, l1);
;                 pv_tile(S1, O1, vf);
	ds_read_b128 v[80:83], v180
	ds_read_b128 v[84:87], v180 offset:4096
	ds_read_b128 v[160:163], v196
	ds_read_b128 v[164:167], v196 offset:4096
	ds_read_b128 v[88:91], v197
	ds_read_b128 v[168:171], v197 offset:4096
	ds_read_b128 v[172:175], v198
	ds_read_b128 v[176:179], v198 offset:4096
	s_waitcnt lgkmcnt(0)
	v_mfma_f32_32x32x16_bf16 v[128:143], v[80:83], v[152:155], v[0:15]
	v_mfma_f32_32x32x16_bf16 v[96:111], v[88:91], v[156:159], v[0:15]
	v_mfma_f32_32x32x16_bf16 v[112:127], v[84:87], v[152:155], v[0:15]
	v_mfma_f32_32x32x16_bf16 v[80:95], v[168:171], v[156:159], v[0:15]
	v_mfma_f32_32x32x16_bf16 v[128:143], v[160:163], v[144:147], v[128:143]
	v_mfma_f32_32x32x16_bf16 v[96:111], v[172:175], v[148:151], v[96:111]
	v_mfma_f32_32x32x16_bf16 v[112:127], v[164:167], v[144:147], v[112:127]
	v_mfma_f32_32x32x16_bf16 v[80:95], v[176:179], v[148:151], v[80:95]
	ds_read_b128 v[188:191], v180 offset:8192
	ds_read_b128 v[184:187], v180 offset:12288
	ds_read_b128 v[180:183], v196 offset:8192
	ds_read_b128 v[176:179], v196 offset:12288
	ds_read_b128 v[172:175], v197 offset:8192
	ds_read_b128 v[168:171], v197 offset:12288
	ds_read_b128 v[164:167], v198 offset:8192
	ds_read_b128 v[160:163], v198 offset:12288
	s_nop 0
	v_exp_f32_e32 v128, v128
	v_exp_f32_e32 v129, v129
	v_exp_f32_e32 v130, v130
	v_exp_f32_e32 v131, v131
	v_exp_f32_e32 v132, v132
	v_exp_f32_e32 v133, v133
	v_exp_f32_e32 v134, v134
	v_exp_f32_e32 v135, v135
	v_add_f32_e64 v196, v128, 0
	v_add_f32_e64 v197, v129, 0
	v_cvt_pk_bf16_f32 v128, v128, v129
	v_add_f32_e64 v196, v130, v196
	v_add_f32_e64 v197, v131, v197
	v_cvt_pk_bf16_f32 v129, v130, v131
	v_cvt_pk_bf16_f32 v130, v132, v133
	v_cvt_pk_bf16_f32 v131, v134, v135
	v_add_f32_e64 v196, v132, v196
	v_add_f32_e64 v197, v133, v197
	v_exp_f32_e32 v136, v136
	s_waitcnt lgkmcnt(0)
	v_mfma_f32_32x32x16_bf16 v[48:63], v[188:191], v[128:131], v[48:63]
	v_exp_f32_e32 v137, v137
	v_exp_f32_e32 v138, v138
	v_exp_f32_e32 v139, v139
	v_exp_f32_e32 v132, v140
	v_exp_f32_e32 v133, v141
	v_exp_f32_e32 v140, v142
	v_exp_f32_e32 v141, v143
	v_mfma_f32_32x32x16_bf16 v[32:47], v[184:187], v[128:131], v[32:47]
	v_add_f32_e64 v134, v134, v196
	v_add_f32_e64 v135, v135, v197
	v_cvt_pk_bf16_f32 v128, v136, v137
	v_cvt_pk_bf16_f32 v129, v138, v139
	v_cvt_pk_bf16_f32 v130, v132, v133
	v_cvt_pk_bf16_f32 v131, v140, v141
	v_add_f32_e64 v134, v136, v134
	v_add_f32_e64 v135, v137, v135
	v_exp_f32_e32 v112, v112
	v_mfma_f32_32x32x16_bf16 v[48:63], v[180:183], v[128:131], v[48:63]
	v_add_f32_e64 v134, v138, v134
	v_add_f32_e64 v135, v139, v135
	v_exp_f32_e32 v113, v113
	v_add_f32_e64 v134, v132, v134
	v_add_f32_e64 v135, v133, v135
	v_exp_f32_e32 v116, v116
	v_add_f32_e64 v132, v140, v134
	v_add_f32_e64 v133, v141, v135
	v_exp_f32_e32 v134, v114
	v_exp_f32_e32 v135, v115
	v_mfma_f32_32x32x16_bf16 v[32:47], v[176:179], v[128:131], v[32:47]
	v_exp_f32_e32 v117, v117
	v_exp_f32_e32 v118, v118
	v_exp_f32_e32 v119, v119
	v_add_f32_e64 v132, v112, v132
	v_add_f32_e64 v133, v113, v133
	v_cvt_pk_bf16_f32 v112, v112, v113
	v_cvt_pk_bf16_f32 v113, v134, v135
	v_cvt_pk_bf16_f32 v114, v116, v117
	v_cvt_pk_bf16_f32 v115, v118, v119
	v_add_f32_e64 v128, v134, v132
	v_add_f32_e64 v129, v135, v133
	v_exp_f32_e32 v120, v120
	v_mfma_f32_32x32x16_bf16 v[48:63], v[172:175], v[112:115], v[48:63]
	v_add_f32_e64 v116, v116, v128
	v_add_f32_e64 v117, v117, v129
	v_exp_f32_e32 v121, v121
	v_add_f32_e64 v116, v118, v116
	v_add_f32_e64 v117, v119, v117
	v_exp_f32_e32 v118, v122
	v_exp_f32_e32 v119, v123
	v_exp_f32_e32 v122, v124
	v_exp_f32_e32 v123, v125
	v_mfma_f32_32x32x16_bf16 v[32:47], v[168:171], v[112:115], v[32:47]
	v_exp_f32_e32 v124, v126
	v_exp_f32_e32 v125, v127
	v_exp_f32_e32 v96, v96
	v_exp_f32_e32 v97, v97
	v_exp_f32_e32 v98, v98
	v_exp_f32_e32 v99, v99
	v_exp_f32_e32 v100, v100
	v_exp_f32_e32 v101, v101
	v_exp_f32_e32 v102, v102
	v_exp_f32_e32 v103, v103
	v_cvt_pk_bf16_f32 v112, v120, v121
	v_cvt_pk_bf16_f32 v113, v118, v119
	v_cvt_pk_bf16_f32 v114, v122, v123
	v_cvt_pk_bf16_f32 v115, v124, v125
	v_exp_f32_e32 v104, v104
	v_exp_f32_e32 v105, v105
	v_mfma_f32_32x32x16_bf16 v[48:63], v[164:167], v[112:115], v[48:63]
	v_exp_f32_e32 v106, v106
	v_exp_f32_e32 v107, v107
	v_exp_f32_e32 v80, v80
	v_exp_f32_e32 v81, v81
	v_exp_f32_e32 v82, v82
	v_exp_f32_e32 v83, v83
	v_exp_f32_e32 v84, v84
	v_mfma_f32_32x32x16_bf16 v[32:47], v[160:163], v[112:115], v[32:47]
	v_add_f32_e64 v112, v96, 0
	v_add_f32_e64 v113, v97, 0
	v_cvt_pk_bf16_f32 v96, v96, v97
	v_add_f32_e64 v112, v98, v112
	v_add_f32_e64 v113, v99, v113
	v_cvt_pk_bf16_f32 v97, v98, v99
	v_cvt_pk_bf16_f32 v98, v100, v101
	v_cvt_pk_bf16_f32 v99, v102, v103
	v_add_f32_e64 v112, v100, v112
	v_add_f32_e64 v113, v101, v113
	v_exp_f32_e32 v100, v108
	v_mfma_f32_32x32x16_bf16 v[64:79], v[188:191], v[96:99], v[64:79]
	v_exp_f32_e32 v101, v109
	v_add_f32_e64 v112, v102, v112
	v_add_f32_e64 v113, v103, v113
	v_exp_f32_e32 v102, v110
	v_exp_f32_e32 v103, v111
	v_add_f32_e64 v112, v104, v112
	v_add_f32_e64 v113, v105, v113
	v_exp_f32_e32 v85, v85
	v_add_f32_e64 v112, v106, v112
	v_add_f32_e64 v113, v107, v113
	v_mfma_f32_32x32x16_bf16 v[16:31], v[184:187], v[96:99], v[16:31]
	v_add_f32_e64 v108, v100, v112
	v_add_f32_e64 v109, v101, v113
	v_cvt_pk_bf16_f32 v98, v100, v101
	v_add_f32_e64 v96, v102, v108
	v_add_f32_e64 v97, v103, v109
	v_cvt_pk_bf16_f32 v99, v102, v103
	v_add_f32_e64 v108, v80, v96
	v_add_f32_e64 v109, v81, v97
	v_cvt_pk_bf16_f32 v96, v104, v105
	v_cvt_pk_bf16_f32 v97, v106, v107
	v_exp_f32_e32 v86, v86
	v_exp_f32_e32 v87, v87
	v_mfma_f32_32x32x16_bf16 v[64:79], v[180:183], v[96:99], v[64:79]
	v_add_f32_e64 v100, v82, v108
	v_add_f32_e64 v101, v83, v109
	v_exp_f32_e32 v88, v88
	v_add_f32_e64 v100, v84, v100
	v_add_f32_e64 v101, v85, v101
	v_exp_f32_e32 v89, v89
	v_cvt_pk_bf16_f32 v80, v80, v81
	v_cvt_pk_bf16_f32 v81, v82, v83
	v_cvt_pk_bf16_f32 v82, v84, v85
	v_mfma_f32_32x32x16_bf16 v[16:31], v[176:179], v[96:99], v[16:31]
	v_cvt_pk_bf16_f32 v83, v86, v87
	v_add_f32_e64 v96, v86, v100
	v_add_f32_e64 v97, v87, v101
	v_exp_f32_e32 v86, v90
	v_exp_f32_e32 v87, v91
	v_exp_f32_e32 v90, v92
	v_exp_f32_e32 v91, v93
	v_exp_f32_e32 v92, v94
	v_mfma_f32_32x32x16_bf16 v[64:79], v[172:175], v[80:83], v[64:79]
	v_exp_f32_e32 v93, v95
	s_addk_i32 s4, 0x4000
	v_add_f32_e64 v84, v88, v96
	v_add_f32_e64 v85, v89, v97
	s_cmp_lg_u32 s35, 2
	s_cselect_b32 s4, s4, 0
	s_add_i32 s4, s4, 32
	s_waitcnt vmcnt(0)
	v_mfma_f32_32x32x16_bf16 v[16:31], v[168:171], v[80:83], v[16:31]
	v_add_f32_e64 v80, v86, v84
	v_add_f32_e64 v81, v87, v85
	v_cvt_pk_bf16_f32 v82, v90, v91
	v_add_f32_e64 v80, v90, v80
	v_add_f32_e64 v81, v91, v81
	v_cvt_pk_bf16_f32 v83, v92, v93
	v_add_f32_e64 v168, v92, v80
	v_add_f32_e64 v169, v93, v81
	v_cvt_pk_bf16_f32 v80, v88, v89
	v_add_u32_e32 v88, s4, v217
	v_cvt_pk_bf16_f32 v81, v86, v87
	v_add_u32_e32 v174, v88, v219
	v_add_u32_e32 v175, v88, v218
	v_add_u32_e32 v176, v88, v216
	v_add_u32_e32 v177, v88, v215
	v_mfma_f32_32x32x16_bf16 v[64:79], v[164:167], v[80:83], v[64:79]
	s_barrier
; template <int KIND>
; DI void attn_unit(const Params& p, int l, int b, int head, int qt, int qcol, int kcol, int vfeat, int gcol, int mixcol,
;                   int t1, int n1, int t2, int n2, char* smem) {
;     ...
;     for (int it = 0; it < nt; ++it) {
;         const int tile = (it < n1) ? t1 + it : t2 + (it - n1);
;         if (it + 1 < nt) asm volatile("s_waitcnt vmcnt(4)" ::: "memory"); else asm volatile("s_waitcnt vmcnt(0)" ::: "memory");
;         __builtin_amdgcn_s_barrier();
;         const char* sk = smem + sc * ATT_SLOT;
;         const char* sv = sk + ATT_V;
;         bool active = true;
;         if (KIND == 2 && tile < 32) active = (tile >= r0w) && (tile < r0w + 8);
;         bf16x8 kf[8], vf[8];
;         if (active) {
; #pragma unroll
;             for (int s = 0; s < 4; ++s)
; #pragma unroll
;                 for (int t = 0; t < 2; ++t) kf[2 * s + t] = *(const bf16x8*)(sk + (32 * t + r) * 128 + (((2 * s + h) ^ xr) << 4));
;         }
;         __builtin_amdgcn_sched_barrier(0);
;         if (it + 2 < nt) { const int nx = (it + 2 < n1) ? t1 + it + 2 : t2 + (it + 2 - n1); KV_ISSUE(nx, sn); }
;         sc = (sc == 2) ? 0 : sc + 1; sn = (sn == 2) ? 0 : sn + 1;
;         __builtin_amdgcn_sched_barrier(0);
;         if (active) {
;     ...
;             if (KIND == 0) {
;                 f32x16 S0[2], S1[2];
; #pragma unroll
;                 for (int t = 0; t < 2; ++t) { S0[t] = MFMA(kf[t], qf[0], cz); S1[t] = MFMA(kf[4 + t], qf[2], cz); }
; #pragma unroll
;                 for (int t = 0; t < 2; ++t) { S0[t] = MFMA(kf[2 + t], qf[1], S0[t]); S1[t] = MFMA(kf[6 + t], qf[3], S1[t]); }
;                 LOAD_VF();
;                 softmax_tile(S0, l0);
;                 pv_tile(S0, O0, vf);
;                 softmax_tile(S1, l1);
;                 pv_tile(S1, O1, vf);
;             } else {
;                 f32x16 S[2];
; #pragma unroll
;                 for (int t = 0; t < 2; ++t) S[t] = MFMA(kf[t], qf[0], cz);
; #pragma unroll
;                 for (int s = 1; s < 4; ++s)
; #pragma unroll
;                     for (int t = 0; t < 2; ++t) S[t] = MFMA(kf[2 * s + t], qf[s], S[t]);
;                 LOAD_VF();
;                 if (KIND == 2 && tile < 32) {
;                     const char* brow = smem + ATT_BIAS + (tile - nrow + 7) * 128;
; #pragma unroll
;                     for (int t = 0; t < 2; ++t)
; #pragma unroll
	ds_read_b128 v[84:87], v174
	ds_read_b128 v[128:131], v174 offset:4096
	ds_read_b128 v[132:135], v175
	ds_read_b128 v[136:139], v175 offset:4096
	ds_read_b128 v[96:99], v176
	ds_read_b128 v[140:143], v176 offset:4096
	ds_read_b128 v[164:167], v177
	ds_read_b128 v[170:173], v177 offset:4096
	v_add_f32_e64 v116, v120, v116
	v_add_f32_e64 v117, v121, v117
	s_nop 0
	v_add_f32_e64 v116, v118, v116
	v_add_f32_e64 v117, v119, v117
	v_mfma_f32_32x32x16_bf16 v[16:31], v[160:163], v[80:83], v[16:31]
	v_add_f32_e64 v116, v122, v116
	v_add_f32_e64 v117, v123, v117
	v_add_f32_e64 v196, v124, v116
	v_add_f32_e64 v197, v125, v117
	s_waitcnt lgkmcnt(0)
	v_mfma_f32_32x32x16_bf16 v[112:127], v[84:87], v[152:155], v[0:15]
	v_mfma_f32_32x32x16_bf16 v[80:95], v[96:99], v[156:159], v[0:15]
	v_mfma_f32_32x32x16_bf16 v[96:111], v[128:131], v[152:155], v[0:15]
	v_mfma_f32_32x32x16_bf16 v[0:15], v[140:143], v[156:159], v[0:15]
	v_mfma_f32_32x32x16_bf16 v[112:127], v[132:135], v[144:147], v[112:127]
	v_mfma_f32_32x32x16_bf16 v[80:95], v[164:167], v[148:151], v[80:95]
	v_mfma_f32_32x32x16_bf16 v[96:111], v[136:139], v[144:147], v[96:111]
	v_mfma_f32_32x32x16_bf16 v[0:15], v[170:173], v[148:151], v[0:15]
	ds_read_b128 v[156:159], v174 offset:8192
	ds_read_b128 v[152:155], v174 offset:12288
	ds_read_b128 v[148:151], v175 offset:8192
	ds_read_b128 v[144:147], v175 offset:12288
	ds_read_b128 v[140:143], v176 offset:8192
	ds_read_b128 v[136:139], v176 offset:12288
	ds_read_b128 v[132:135], v177 offset:8192
	ds_read_b128 v[128:131], v177 offset:12288
	s_nop 0
	v_exp_f32_e32 v112, v112
	v_exp_f32_e32 v113, v113
	v_exp_f32_e32 v114, v114
	v_exp_f32_e32 v115, v115
	v_exp_f32_e32 v116, v116
	v_exp_f32_e32 v117, v117
	v_exp_f32_e32 v118, v118
	v_exp_f32_e32 v119, v119
	v_add_f32_e64 v160, v112, 0
	v_add_f32_e64 v161, v113, 0
	v_cvt_pk_bf16_f32 v112, v112, v113
	v_add_f32_e64 v160, v114, v160
	v_add_f32_e64 v161, v115, v161
	v_cvt_pk_bf16_f32 v113, v114, v115
	v_cvt_pk_bf16_f32 v114, v116, v117
	v_cvt_pk_bf16_f32 v115, v118, v119
	v_exp_f32_e32 v120, v120
	v_exp_f32_e32 v121, v121
	s_waitcnt lgkmcnt(0)
	v_mfma_f32_32x32x16_bf16 v[48:63], v[156:159], v[112:115], v[48:63]
	v_exp_f32_e32 v122, v122
	v_exp_f32_e32 v123, v123
	v_exp_f32_e32 v124, v124
	v_exp_f32_e32 v125, v125
	v_exp_f32_e32 v126, v126
	v_exp_f32_e32 v127, v127
	v_add_f32_e64 v160, v116, v160
	v_add_f32_e64 v161, v117, v161
	v_mfma_f32_32x32x16_bf16 v[32:47], v[152:155], v[112:115], v[32:47]
	v_add_f32_e64 v160, v118, v160
	v_add_f32_e64 v161, v119, v161
	v_exp_f32_e32 v118, v96
	v_add_f32_e64 v160, v120, v160
	v_add_f32_e64 v161, v121, v161
	v_exp_f32_e32 v119, v97
	v_add_f32_e64 v116, v122, v160
	v_add_f32_e64 v117, v123, v161
	v_exp_f32_e32 v160, v98
	v_exp_f32_e32 v161, v99
	v_cvt_pk_bf16_f32 v96, v120, v121
	v_cvt_pk_bf16_f32 v97, v122, v123
	v_cvt_pk_bf16_f32 v98, v124, v125
	v_cvt_pk_bf16_f32 v99, v126, v127
	v_add_f32_e64 v116, v124, v116
	v_add_f32_e64 v117, v125, v117
	v_exp_f32_e32 v100, v100
	v_mfma_f32_32x32x16_bf16 v[48:63], v[148:151], v[96:99], v[48:63]
	v_exp_f32_e32 v101, v101
	v_add_f32_e64 v116, v126, v116
	v_add_f32_e64 v117, v127, v117
	v_exp_f32_e32 v102, v102
	v_exp_f32_e32 v103, v103
	v_add_f32_e64 v112, v118, v116
	v_add_f32_e64 v113, v119, v117
	v_exp_f32_e32 v104, v104
	v_exp_f32_e32 v105, v105
	v_mfma_f32_32x32x16_bf16 v[32:47], v[144:147], v[96:99], v[32:47]
	v_add_f32_e64 v112, v160, v112
	v_add_f32_e64 v113, v161, v113
	v_exp_f32_e32 v106, v106
	v_exp_f32_e32 v107, v107
	v_add_f32_e64 v112, v100, v112
	v_add_f32_e64 v113, v101, v113
	v_exp_f32_e32 v108, v108
	v_add_f32_e64 v112, v102, v112
	v_add_f32_e64 v113, v103, v113
	v_cvt_pk_bf16_f32 v96, v118, v119
	v_cvt_pk_bf16_f32 v97, v160, v161
	v_cvt_pk_bf16_f32 v98, v100, v101
	v_cvt_pk_bf16_f32 v99, v102, v103
	v_exp_f32_e32 v109, v109
	v_exp_f32_e32 v100, v110
	v_mfma_f32_32x32x16_bf16 v[48:63], v[140:143], v[96:99], v[48:63]
	v_exp_f32_e32 v101, v111
	v_add_f32_e64 v102, v104, v112
	v_add_f32_e64 v103, v105, v113
	v_exp_f32_e32 v84, v84
	v_add_f32_e64 v102, v106, v102
	v_add_f32_e64 v103, v107, v103
	v_exp_f32_e32 v85, v85
	v_add_f32_e64 v102, v108, v102
	v_add_f32_e64 v103, v109, v103
	v_exp_f32_e32 v86, v86
	v_mfma_f32_32x32x16_bf16 v[32:47], v[136:139], v[96:99], v[32:47]
	v_cvt_pk_bf16_f32 v96, v104, v105
	v_exp_f32_e32 v104, v80
	v_exp_f32_e32 v105, v81
	v_cvt_pk_bf16_f32 v97, v106, v107
	v_exp_f32_e32 v106, v82
	v_exp_f32_e32 v107, v83
	v_exp_f32_e32 v87, v87
	v_add_f32_e64 v102, v100, v102
	v_add_f32_e64 v103, v101, v103
	v_add_f32_e64 v82, v104, 0
	v_add_f32_e64 v83, v105, 0
	v_exp_f32_e32 v88, v88
	v_exp_f32_e32 v89, v89
	v_mov_b32_e32 v110, v196
	v_mov_b32_e32 v111, v102
	v_mov_b32_e32 v102, v197
	v_add_f32_e64 v82, v106, v82
	v_add_f32_e64 v83, v107, v83
	v_exp_f32_e32 v90, v90
	v_exp_f32_e32 v91, v91
	v_cvt_pk_bf16_f32 v99, v100, v101
	v_add_f32_e64 v100, v110, v102
	v_add_f32_e64 v101, v111, v103
	v_add_f32_e64 v82, v84, v82
	v_add_f32_e64 v83, v85, v83
	v_exp_f32_e32 v92, v92
	v_exp_f32_e32 v93, v93
	s_add_u32 s7, s29, s7
	v_pk_add_f32 v[102:103], v[194:195], v[100:101] op_sel:[1,0] op_sel_hi:[0,1]
	v_add_f32_e64 v82, v86, v82
	v_add_f32_e64 v83, v87, v83
	s_addc_u32 s9, s9, 0
	s_add_i32 s8, s8, 0x36000
	s_lshl_b64 s[4:5], s[60:61], 2
	v_cvt_pk_bf16_f32 v98, v108, v109
	v_pk_add_f32 v[80:81], v[102:103], v[100:101] op_sel:[0,1] op_sel_hi:[1,0]
	v_add_f32_e64 v82, v88, v82
	v_add_f32_e64 v83, v89, v83
	s_add_u32 s4, s50, s4
	v_mfma_f32_32x32x16_bf16 v[48:63], v[132:135], v[96:99], v[48:63]
	v_mov_b32_e32 v81, v200
	s_addc_u32 s5, s51, s5
	v_cvt_pk_bf16_f32 v84, v84, v85
	v_cvt_pk_bf16_f32 v85, v86, v87
	v_exp_f32_e32 v94, v94
; DI int otid() { int t = threadIdx.x; asm volatile("" : "+v"(t)); return t; }
; DI float xsum32(float x) { const unsigned u = __float_as_uint(x); const auto r2 = __builtin_amdgcn_permlane32_swap(u, u, false, false); return __uint_as_float(r2[0]) + __uint_as_float(r2[1]); }
; template <int KIND>
; DI void attn_unit(const Params& p, int l, int b, int head, int qt, int qcol, int kcol, int vfeat, int gcol, int mixcol,
;                   int t1, int n1, int t2, int n2, char* smem) {
;     ...
;     l0 = xsum32(l0);
;     const float inv0 = 1.f / l0;
;     const int tid_e = otid();
;     const size_t qrow_e = (size_t)b * TPB + qt * 128 + 32 * (tid_e >> 6) + (tid_e & 31);
;     bf16_t* orow = p.hmix + ((size_t)(mixcol >> 5) * NTOK + qrow_e) * 32;
;     const bf16_t* grow = p.qkv + ((size_t)(gcol >> 6) * NTOK + qrow_e) * 64;
;     if (KIND == 0) {
;         l1 = xsum32(l1);
;         const float lam = p.lam[l];
;         const float inv1 = lam / l1;
;         float ss = 0.f;
; #pragma unroll
;         for (int t = 0; t < 2; ++t)
; #pragma unroll
;             for (int e = 0; e < 16; ++e) { const float o = O0[t][e] * inv0 - O1[t][e] * inv1; O0[t][e] = o; ss += o * o; }
;         ss = xsum32(ss);
;         const float rstd = rsqrtf(ss * (1.f / 64.f) + EPS) * p.lam[4 + l];
	v_exp_f32_e32 v95, v95
	v_mfma_f32_32x32x16_bf16 v[32:47], v[128:131], v[96:99], v[32:47]
	v_add_f32_e64 v96, v90, v82
	v_add_f32_e64 v97, v91, v83
	v_exp_f32_e32 v98, v0
	v_exp_f32_e32 v99, v1
	v_add_f32_e64 v0, v92, v96
	v_add_f32_e64 v1, v93, v97
	global_load_dword v96, v193, s[4:5]
	v_cvt_pk_bf16_f32 v82, v104, v105
	v_cvt_pk_bf16_f32 v83, v106, v107
	v_exp_f32_e32 v100, v2
	v_exp_f32_e32 v101, v3
	v_mfma_f32_32x32x16_bf16 v[64:79], v[156:159], v[82:85], v[64:79]
	v_exp_f32_e32 v86, v4
	v_exp_f32_e32 v87, v5
	v_cvt_pk_bf16_f32 v2, v88, v89
	v_cvt_pk_bf16_f32 v3, v90, v91
	v_cvt_pk_bf16_f32 v4, v92, v93
	v_cvt_pk_bf16_f32 v5, v94, v95
	v_add_f32_e64 v0, v94, v0
	v_add_f32_e64 v1, v95, v1
	v_mfma_f32_32x32x16_bf16 v[16:31], v[152:155], v[82:85], v[16:31]
	v_exp_f32_e32 v6, v6
	v_exp_f32_e32 v7, v7
	v_add_f32_e64 v0, v98, v0
	v_add_f32_e64 v1, v99, v1
	v_exp_f32_e32 v8, v8
	v_exp_f32_e32 v9, v9
	v_add_f32_e64 v0, v100, v0
	v_add_f32_e64 v1, v101, v1
	v_exp_f32_e32 v10, v10
	v_mfma_f32_32x32x16_bf16 v[64:79], v[148:151], v[2:5], v[64:79]
	v_exp_f32_e32 v11, v11
	v_add_f32_e64 v82, v86, v0
	v_add_f32_e64 v83, v87, v1
	v_exp_f32_e32 v12, v12
	v_exp_f32_e32 v13, v13
	v_add_f32_e64 v82, v6, v82
	v_add_f32_e64 v83, v7, v83
	v_ashrrev_i32_e32 v0, 1, v81
	v_and_b32_e32 v0, 0xffffffe0, v0
	v_mfma_f32_32x32x16_bf16 v[16:31], v[144:147], v[2:5], v[16:31]
	v_cvt_pk_bf16_f32 v5, v6, v7
	v_exp_f32_e32 v6, v14
	v_exp_f32_e32 v7, v15
	v_add_f32_e64 v14, v8, v82
	v_add_f32_e64 v15, v9, v83
	v_cvt_pk_bf16_f32 v2, v98, v99
	v_add_f32_e64 v14, v10, v14
	v_add_f32_e64 v15, v11, v15
	v_cvt_pk_bf16_f32 v3, v100, v101
	v_cvt_pk_bf16_f32 v4, v86, v87
	v_add_f32_e64 v14, v12, v14
	v_add_f32_e64 v15, v13, v15
	v_ashrrev_i32_e32 v1, 31, v0
	v_mfma_f32_32x32x16_bf16 v[64:79], v[140:143], v[2:5], v[64:79]
	v_add_f32_e64 v14, v6, v14
	v_add_f32_e64 v15, v7, v15
	v_and_or_b32 v84, v81, 31, s7
	v_mov_b32_e32 v85, s9
	v_lshl_add_u64 v[84:85], v[84:85], 0, v[0:1]
	s_mov_b32 s9, s75
	v_lshl_add_u64 v[0:1], v[84:85], 0, s[8:9]
	v_mov_b32_e32 v82, v168
	v_mfma_f32_32x32x16_bf16 v[16:31], v[136:139], v[2:5], v[16:31]
	v_cvt_pk_bf16_f32 v5, v6, v7
	v_mov_b32_e32 v6, v80
	s_nop 1
	v_permlane32_swap_b32_e32 v80, v6
	v_cvt_pk_bf16_f32 v2, v8, v9
	v_add_f32_e32 v8, v80, v6
	v_div_scale_f32 v9, s[8:9], v8, v8, 1.0
	v_cvt_pk_bf16_f32 v3, v10, v11
	v_rcp_f32_e32 v10, v9
	v_cvt_pk_bf16_f32 v4, v12, v13
	v_mov_b32_e32 v83, v14
	v_mov_b32_e32 v14, v169
	v_mfma_f32_32x32x16_bf16 v[64:79], v[132:135], v[2:5], v[64:79]
	v_add_f32_e64 v14, v82, v14
	v_add_f32_e64 v15, v83, v15
	global_load_dword v80, v193, s[4:5] offset:16
	v_add_f32_e64 v6, v194, v14
	v_add_f32_e64 v7, v195, v15
	v_lshlrev_b64 v[0:1], 7, v[0:1]
	v_pk_add_f32 v[6:7], v[6:7], v[14:15] op_sel:[0,1] op_sel_hi:[1,0]
	v_lshl_add_u64 v[0:1], s[40:41], 0, v[0:1]
	v_lshlrev_b32_e32 v88, 3, v214
	v_mfma_f32_32x32x16_bf16 v[16:31], v[128:131], v[2:5], v[16:31]
	v_fma_f32 v2, -v9, v10, 1.0
	v_fmac_f32_e32 v10, v2, v10
	v_div_scale_f32 v2, vcc, 1.0, v8, 1.0
	v_mul_f32_e32 v3, v2, v10
	v_fma_f32 v4, -v9, v3, v2
	v_fmac_f32_e32 v3, v4, v10
	v_fma_f32 v2, -v9, v3, v2
	v_div_fmas_f32 v2, v2, v10, v3
	v_div_fixup_f32 v8, v2, v8, 1.0
	v_mov_b32_e32 v2, v6
	s_nop 1
	v_permlane32_swap_b32_e32 v6, v2
	v_add_f32_e32 v4, v6, v2
	s_waitcnt vmcnt(0)
	v_div_scale_f32 v5, s[4:5], v4, v4, v96
	v_rcp_f32_e32 v6, v5
	v_mov_b32_e32 v89, v193
	v_lshl_add_u64 v[0:1], v[0:1], 0, v[88:89]
	s_mul_i32 s6, s6, 0x9000
	v_fma_f32 v7, -v5, v6, 1.0
	s_mov_b32 s7, s75
	v_fmac_f32_e32 v6, v7, v6
	v_div_scale_f32 v7, vcc, v96, v4, v96
	global_load_dwordx2 v[90:91], v[0:1], off
	v_lshl_add_u64 v[2:3], v[84:85], 0, s[6:7]
	v_mul_f32_e32 v9, v7, v6
	s_load_dwordx2 s[4:5], s[0:1], 0xb8
	s_load_dwordx2 s[6:7], s[0:1], 0x78
	v_fma_f32 v10, -v5, v9, v7
	v_fmac_f32_e32 v9, v10, v6
	v_fma_f32 v5, -v5, v9, v7
	v_lshlrev_b64 v[2:3], 6, v[2:3]
	v_div_fmas_f32 v5, v5, v6, v9
	v_div_fixup_f32 v10, v5, v4, v96
	s_waitcnt lgkmcnt(0)
	v_lshl_add_u64 v[2:3], s[4:5], 0, v[2:3]
	s_add_u32 s4, s6, s46
	s_addc_u32 s5, s7, s47
	v_pk_mul_f32 v[4:5], v[66:67], v[10:11] op_sel_hi:[1,0]
	v_pk_mul_f32 v[16:17], v[16:17], v[10:11] op_sel_hi:[1,0]
	v_pk_fma_f32 v[14:15], v[50:51], v[8:9], v[4:5] op_sel_hi:[1,0,1] neg_lo:[0,0,1] neg_hi:[0,0,1]
	global_load_dwordx4 v[4:7], v192, s[4:5]
	v_pk_mul_f32 v[50:51], v[64:65], v[10:11] op_sel_hi:[1,0]
	v_mul_f32_e32 v64, v15, v15
	v_pk_fma_f32 v[48:49], v[48:49], v[8:9], v[50:51] op_sel_hi:[1,0,1] neg_lo:[0,0,1] neg_hi:[0,0,1]
	v_pk_mul_f32 v[18:19], v[18:19], v[10:11] op_sel_hi:[1,0]
	v_mul_f32_e32 v50, v49, v49
	v_pk_fma_f32 v[50:51], v[48:49], v[48:49], v[50:51] op_sel_hi:[1,1,0]
	v_pk_fma_f32 v[16:17], v[32:33], v[8:9], v[16:17] op_sel_hi:[1,0,1] neg_lo:[0,0,1] neg_hi:[0,0,1]
	v_pk_fma_f32 v[50:51], v[14:15], v[14:15], v[50:51]
	v_pk_fma_f32 v[18:19], v[34:35], v[8:9], v[18:19] op_sel_hi:[1,0,1] neg_lo:[0,0,1] neg_hi:[0,0,1]
	v_pk_add_f32 v[50:51], v[64:65], v[50:51] op_sel_hi:[0,1]
	v_pk_mul_f32 v[64:65], v[70:71], v[10:11] op_sel_hi:[1,0]
	v_mul_f32_e32 v34, v17, v17
	v_pk_fma_f32 v[54:55], v[54:55], v[8:9], v[64:65] op_sel_hi:[1,0,1] neg_lo:[0,0,1] neg_hi:[0,0,1]
	v_pk_mul_f32 v[64:65], v[68:69], v[10:11] op_sel_hi:[1,0]
	v_pk_mul_f32 v[20:21], v[20:21], v[10:11] op_sel_hi:[1,0]
	v_pk_fma_f32 v[52:53], v[52:53], v[8:9], v[64:65] op_sel_hi:[1,0,1] neg_lo:[0,0,1] neg_hi:[0,0,1]
	v_pk_fma_f32 v[20:21], v[36:37], v[8:9], v[20:21] op_sel_hi:[1,0,1] neg_lo:[0,0,1] neg_hi:[0,0,1]
	v_pk_fma_f32 v[50:51], v[52:53], v[52:53], v[50:51]
	v_mul_f32_e32 v64, v53, v53
	v_pk_add_f32 v[50:51], v[64:65], v[50:51] op_sel_hi:[0,1]
	v_pk_fma_f32 v[50:51], v[54:55], v[54:55], v[50:51]
; DI unsigned pk2(float a, float b) { f2_t v = {a, b}; bf2_t r = __builtin_convertvector(v, bf2_t); return __builtin_bit_cast(unsigned, r); }
; DI float bf2f(bf16_t v) { return __uint_as_float(((unsigned)v) << 16); }
; DI float xsum32(float x) { const unsigned u = __float_as_uint(x); const auto r2 = __builtin_amdgcn_permlane32_swap(u, u, false, false); return __uint_as_float(r2[0]) + __uint_as_float(r2[1]); }
; template <int KIND>
; DI void attn_unit(const Params& p, int l, int b, int head, int qt, int qcol, int kcol, int vfeat, int gcol, int mixcol,
;                   int t1, int n1, int t2, int n2, char* smem) {
;     ...
;         float ss = 0.f;
; #pragma unroll
;         for (int t = 0; t < 2; ++t)
; #pragma unroll
;             for (int e = 0; e < 16; ++e) { const float o = O0[t][e] * inv0 - O1[t][e] * inv1; O0[t][e] = o; ss += o * o; }
;         ss = xsum32(ss);
;         const float rstd = rsqrtf(ss * (1.f / 64.f) + EPS) * p.lam[4 + l];
;         const float* sw = p.subln + l * 64;
; #pragma unroll
;         for (int t = 0; t < 2; ++t)
; #pragma unroll
;             for (int q = 0; q < 4; ++q) {
;                 const int f = 32 * t + 8 * q + 4 * h;
;                 const float4 w4 = *(const float4*)(sw + f);
;                 const uint2 gg = *(const uint2*)(grow + f);
;                 const float g0 = bf2f((bf16_t)(gg.x & 0xffff)), g1 = bf2f((bf16_t)(gg.x >> 16)), g2 = bf2f((bf16_t)(gg.y & 0xffff)), g3 = bf2f((bf16_t)(gg.y >> 16));
;                 uint2 o;
;                 o.x = pk2(O0[t][4 * q + 0] * rstd * w4.x * g0, O0[t][4 * q + 1] * rstd * w4.y * g1);
;                 o.y = pk2(O0[t][4 * q + 2] * rstd * w4.z * g2, O0[t][4 * q + 3] * rstd * w4.w * g3);
;                 *(uint2*)(orow + (size_t)t * NTOK * 32 + 8 * q + 4 * h) = o;
	v_mul_f32_e32 v64, v55, v55
	v_pk_add_f32 v[50:51], v[64:65], v[50:51] op_sel_hi:[0,1]
	v_pk_mul_f32 v[64:65], v[74:75], v[10:11] op_sel_hi:[1,0]
	v_pk_mul_f32 v[22:23], v[22:23], v[10:11] op_sel_hi:[1,0]
	v_pk_fma_f32 v[58:59], v[58:59], v[8:9], v[64:65] op_sel_hi:[1,0,1] neg_lo:[0,0,1] neg_hi:[0,0,1]
	v_pk_mul_f32 v[64:65], v[72:73], v[10:11] op_sel_hi:[1,0]
	v_pk_fma_f32 v[22:23], v[38:39], v[8:9], v[22:23] op_sel_hi:[1,0,1] neg_lo:[0,0,1] neg_hi:[0,0,1]
	v_pk_fma_f32 v[56:57], v[56:57], v[8:9], v[64:65] op_sel_hi:[1,0,1] neg_lo:[0,0,1] neg_hi:[0,0,1]
	v_pk_mul_f32 v[24:25], v[24:25], v[10:11] op_sel_hi:[1,0]
	v_pk_fma_f32 v[50:51], v[56:57], v[56:57], v[50:51]
	v_mul_f32_e32 v64, v57, v57
	v_pk_add_f32 v[50:51], v[64:65], v[50:51] op_sel_hi:[0,1]
	v_pk_fma_f32 v[50:51], v[58:59], v[58:59], v[50:51]
	v_mul_f32_e32 v64, v59, v59
	v_pk_add_f32 v[50:51], v[64:65], v[50:51] op_sel_hi:[0,1]
	v_pk_mul_f32 v[64:65], v[78:79], v[10:11] op_sel_hi:[1,0]
	v_pk_fma_f32 v[24:25], v[40:41], v[8:9], v[24:25] op_sel_hi:[1,0,1] neg_lo:[0,0,1] neg_hi:[0,0,1]
	v_pk_fma_f32 v[62:63], v[62:63], v[8:9], v[64:65] op_sel_hi:[1,0,1] neg_lo:[0,0,1] neg_hi:[0,0,1]
	v_pk_mul_f32 v[64:65], v[76:77], v[10:11] op_sel_hi:[1,0]
	v_pk_mul_f32 v[26:27], v[26:27], v[10:11] op_sel_hi:[1,0]
	v_pk_fma_f32 v[60:61], v[60:61], v[8:9], v[64:65] op_sel_hi:[1,0,1] neg_lo:[0,0,1] neg_hi:[0,0,1]
	v_pk_fma_f32 v[26:27], v[42:43], v[8:9], v[26:27] op_sel_hi:[1,0,1] neg_lo:[0,0,1] neg_hi:[0,0,1]
	v_pk_fma_f32 v[50:51], v[60:61], v[60:61], v[50:51]
	v_mul_f32_e32 v64, v61, v61
	v_pk_add_f32 v[50:51], v[64:65], v[50:51] op_sel_hi:[0,1]
	v_pk_fma_f32 v[50:51], v[62:63], v[62:63], v[50:51]
	v_mul_f32_e32 v64, v63, v63
	v_pk_add_f32 v[50:51], v[64:65], v[50:51] op_sel_hi:[0,1]
	v_pk_fma_f32 v[32:33], v[16:17], v[16:17], v[50:51]
	v_pk_mul_f32 v[30:31], v[30:31], v[10:11] op_sel_hi:[1,0]
	v_pk_add_f32 v[32:33], v[34:35], v[32:33] op_sel_hi:[0,1]
	v_pk_fma_f32 v[32:33], v[18:19], v[18:19], v[32:33]
	v_mul_f32_e32 v34, v19, v19
	v_pk_add_f32 v[32:33], v[34:35], v[32:33] op_sel_hi:[0,1]
	v_pk_fma_f32 v[32:33], v[20:21], v[20:21], v[32:33]
	v_mul_f32_e32 v34, v21, v21
	v_pk_add_f32 v[32:33], v[34:35], v[32:33] op_sel_hi:[0,1]
	v_pk_fma_f32 v[32:33], v[22:23], v[22:23], v[32:33]
	v_mul_f32_e32 v34, v23, v23
	v_pk_add_f32 v[32:33], v[34:35], v[32:33] op_sel_hi:[0,1]
	v_pk_fma_f32 v[32:33], v[24:25], v[24:25], v[32:33]
	v_mul_f32_e32 v34, v25, v25
	v_pk_add_f32 v[32:33], v[34:35], v[32:33] op_sel_hi:[0,1]
	v_pk_fma_f32 v[32:33], v[26:27], v[26:27], v[32:33]
	v_mul_f32_e32 v34, v27, v27
	v_pk_mul_f32 v[10:11], v[28:29], v[10:11] op_sel_hi:[1,0]
	v_pk_add_f32 v[32:33], v[34:35], v[32:33] op_sel_hi:[0,1]
	v_pk_fma_f32 v[30:31], v[46:47], v[8:9], v[30:31] op_sel_hi:[1,0,1] neg_lo:[0,0,1] neg_hi:[0,0,1]
	v_pk_fma_f32 v[8:9], v[44:45], v[8:9], v[10:11] op_sel_hi:[1,0,1] neg_lo:[0,0,1] neg_hi:[0,0,1]
	s_waitcnt vmcnt(1)
	v_lshlrev_b32_e32 v12, 16, v90
	v_pk_fma_f32 v[10:11], v[8:9], v[8:9], v[32:33]
	v_mul_f32_e32 v28, v9, v9
	v_pk_add_f32 v[10:11], v[28:29], v[10:11] op_sel_hi:[0,1]
	v_pk_fma_f32 v[10:11], v[30:31], v[30:31], v[10:11]
	v_mul_f32_e32 v28, v31, v31
	v_pk_add_f32 v[10:11], v[28:29], v[10:11] op_sel_hi:[0,1]
	v_mov_b32_e32 v11, v10
	s_nop 1
	v_permlane32_swap_b32_e32 v10, v11
	v_add_f32_e32 v10, v10, v11
	v_fmamk_f32 v10, v10, 0x3c800000, v201
	v_mul_f32_e32 v11, 0x4b800000, v10
	v_cmp_gt_f32_e32 vcc, s87, v10
	v_and_b32_e32 v13, 0xffff0000, v90
	v_lshl_add_u64 v[2:3], v[2:3], 0, v[88:89]
	v_cndmask_b32_e32 v10, v10, v11, vcc
	v_rsq_f32_e32 v28, v10
	v_lshlrev_b32_e32 v10, 16, v91
	v_and_b32_e32 v11, 0xffff0000, v91
	s_mov_b32 s6, 0x120000
	v_mul_f32_e32 v29, 0x45800000, v28
	v_cndmask_b32_e32 v28, v28, v29, vcc
	v_mul_f32_e32 v28, v80, v28
	v_pk_mul_f32 v[32:33], v[48:49], v[28:29] op_sel_hi:[1,0]
	s_waitcnt vmcnt(0)
	v_pk_mul_f32 v[4:5], v[4:5], v[32:33]
	s_nop 0
	v_pk_mul_f32 v[4:5], v[4:5], v[12:13]
	v_pk_mul_f32 v[12:13], v[14:15], v[28:29] op_sel_hi:[1,0]
	v_cvt_pk_bf16_f32 v4, v4, v5
	v_pk_mul_f32 v[6:7], v[6:7], v[12:13]
	v_pk_mul_f32 v[14:15], v[52:53], v[28:29] op_sel_hi:[1,0]
	v_pk_mul_f32 v[6:7], v[6:7], v[10:11]
	s_nop 0
	v_cvt_pk_bf16_f32 v5, v6, v7
	global_store_dwordx2 v[2:3], v[4:5], off
	global_load_dwordx2 v[10:11], v[0:1], off offset:16
	s_nop 0
	global_load_dwordx4 v[4:7], v192, s[4:5] offset:32
	s_waitcnt vmcnt(1)
	v_lshlrev_b32_e32 v12, 16, v10
	v_and_b32_e32 v13, 0xffff0000, v10
	s_waitcnt vmcnt(0)
; DI unsigned pk2(float a, float b) { f2_t v = {a, b}; bf2_t r = __builtin_convertvector(v, bf2_t); return __builtin_bit_cast(unsigned, r); }
; DI float bf2f(bf16_t v) { return __uint_as_float(((unsigned)v) << 16); }
; template <int KIND>
; DI void attn_unit(const Params& p, int l, int b, int head, int qt, int qcol, int kcol, int vfeat, int gcol, int mixcol,
;                   int t1, int n1, int t2, int n2, char* smem) {
;     ...
;         const float* sw = p.subln + l * 64;
; #pragma unroll
;         for (int t = 0; t < 2; ++t)
; #pragma unroll
;             for (int q = 0; q < 4; ++q) {
;                 const int f = 32 * t + 8 * q + 4 * h;
;                 const float4 w4 = *(const float4*)(sw + f);
;                 const uint2 gg = *(const uint2*)(grow + f);
;                 const float g0 = bf2f((bf16_t)(gg.x & 0xffff)), g1 = bf2f((bf16_t)(gg.x >> 16)), g2 = bf2f((bf16_t)(gg.y & 0xffff)), g3 = bf2f((bf16_t)(gg.y >> 16));
;                 uint2 o;
;                 o.x = pk2(O0[t][4 * q + 0] * rstd * w4.x * g0, O0[t][4 * q + 1] * rstd * w4.y * g1);
;                 o.y = pk2(O0[t][4 * q + 2] * rstd * w4.z * g2, O0[t][4 * q + 3] * rstd * w4.w * g3);
;                 *(uint2*)(orow + (size_t)t * NTOK * 32 + 8 * q + 4 * h) = o;
;             }
	v_pk_mul_f32 v[4:5], v[4:5], v[14:15]
	v_lshlrev_b32_e32 v10, 16, v11
	v_pk_mul_f32 v[4:5], v[4:5], v[12:13]
	v_pk_mul_f32 v[12:13], v[54:55], v[28:29] op_sel_hi:[1,0]
	v_and_b32_e32 v11, 0xffff0000, v11
	v_pk_mul_f32 v[6:7], v[12:13], v[6:7]
	v_cvt_pk_bf16_f32 v4, v4, v5
	v_pk_mul_f32 v[6:7], v[6:7], v[10:11]
	v_pk_mul_f32 v[14:15], v[56:57], v[28:29] op_sel_hi:[1,0]
	v_cvt_pk_bf16_f32 v5, v6, v7
	global_store_dwordx2 v[2:3], v[4:5], off offset:16
	global_load_dwordx2 v[10:11], v[0:1], off offset:32
	s_nop 0
	global_load_dwordx4 v[4:7], v192, s[4:5] offset:64
	s_waitcnt vmcnt(1)
	v_lshlrev_b32_e32 v12, 16, v10
	v_and_b32_e32 v13, 0xffff0000, v10
	s_waitcnt vmcnt(0)
	v_pk_mul_f32 v[4:5], v[14:15], v[4:5]
	v_lshlrev_b32_e32 v10, 16, v11
	v_pk_mul_f32 v[4:5], v[4:5], v[12:13]
	v_pk_mul_f32 v[12:13], v[58:59], v[28:29] op_sel_hi:[1,0]
	v_and_b32_e32 v11, 0xffff0000, v11
	v_pk_mul_f32 v[6:7], v[12:13], v[6:7]
	v_cvt_pk_bf16_f32 v4, v4, v5
	v_pk_mul_f32 v[6:7], v[6:7], v[10:11]
	v_pk_mul_f32 v[12:13], v[60:61], v[28:29] op_sel_hi:[1,0]
	v_cvt_pk_bf16_f32 v5, v6, v7
	global_store_dwordx2 v[2:3], v[4:5], off offset:32
	global_load_dwordx2 v[10:11], v[0:1], off offset:48
	s_nop 0
	global_load_dwordx4 v[4:7], v192, s[4:5] offset:96
	v_pk_mul_f32 v[14:15], v[62:63], v[28:29] op_sel_hi:[1,0]
	s_waitcnt vmcnt(1)
	v_lshlrev_b32_e32 v32, 16, v10
	v_and_b32_e32 v33, 0xffff0000, v10
	v_lshlrev_b32_e32 v10, 16, v11
	v_and_b32_e32 v11, 0xffff0000, v11
	s_waitcnt vmcnt(0)
	v_pk_mul_f32 v[4:5], v[12:13], v[4:5]
	v_pk_mul_f32 v[6:7], v[14:15], v[6:7]
	v_pk_mul_f32 v[4:5], v[4:5], v[32:33]
	v_pk_mul_f32 v[6:7], v[6:7], v[10:11]
	v_cvt_pk_bf16_f32 v4, v4, v5
	v_cvt_pk_bf16_f32 v5, v6, v7
	global_store_dwordx2 v[2:3], v[4:5], off offset:48
	global_load_dwordx2 v[10:11], v[0:1], off offset:64
	s_nop 0
	global_load_dwordx4 v[4:7], v192, s[4:5] offset:128
	v_add_co_u32_e32 v12, vcc, s6, v2
	v_pk_mul_f32 v[14:15], v[18:19], v[28:29] op_sel_hi:[1,0]
	s_nop 0
	v_addc_co_u32_e32 v13, vcc, 0, v3, vcc
	v_pk_mul_f32 v[2:3], v[16:17], v[28:29] op_sel_hi:[1,0]
	s_waitcnt vmcnt(1)
	v_lshlrev_b32_e32 v16, 16, v10
	v_and_b32_e32 v17, 0xffff0000, v10
	v_lshlrev_b32_e32 v10, 16, v11
	v_and_b32_e32 v11, 0xffff0000, v11
	s_waitcnt vmcnt(0)
	v_pk_mul_f32 v[2:3], v[2:3], v[4:5]
	v_pk_mul_f32 v[4:5], v[14:15], v[6:7]
	v_pk_mul_f32 v[2:3], v[2:3], v[16:17]
	v_pk_mul_f32 v[4:5], v[4:5], v[10:11]
	v_cvt_pk_bf16_f32 v2, v2, v3
	v_cvt_pk_bf16_f32 v3, v4, v5
	global_store_dwordx2 v[12:13], v[2:3], off
	global_load_dwordx2 v[6:7], v[0:1], off offset:80
	s_nop 0
	global_load_dwordx4 v[2:5], v192, s[4:5] offset:160
	v_pk_mul_f32 v[10:11], v[20:21], v[28:29] op_sel_hi:[1,0]
	v_pk_mul_f32 v[14:15], v[22:23], v[28:29] op_sel_hi:[1,0]
	s_waitcnt vmcnt(1)
	v_lshlrev_b32_e32 v16, 16, v6
	v_and_b32_e32 v17, 0xffff0000, v6
	v_lshlrev_b32_e32 v6, 16, v7
	v_and_b32_e32 v7, 0xffff0000, v7
	s_waitcnt vmcnt(0)
	v_pk_mul_f32 v[2:3], v[10:11], v[2:3]
	v_pk_mul_f32 v[4:5], v[14:15], v[4:5]
	v_pk_mul_f32 v[2:3], v[2:3], v[16:17]
	v_pk_mul_f32 v[4:5], v[4:5], v[6:7]
	v_cvt_pk_bf16_f32 v2, v2, v3
	v_cvt_pk_bf16_f32 v3, v4, v5
	global_store_dwordx2 v[12:13], v[2:3], off offset:16
	global_load_dwordx2 v[6:7], v[0:1], off offset:96
	s_nop 0
	global_load_dwordx4 v[2:5], v192, s[4:5] offset:192
	v_pk_mul_f32 v[10:11], v[24:25], v[28:29] op_sel_hi:[1,0]
	v_pk_mul_f32 v[14:15], v[26:27], v[28:29] op_sel_hi:[1,0]
	s_waitcnt vmcnt(1)
	v_lshlrev_b32_e32 v16, 16, v6
	v_and_b32_e32 v17, 0xffff0000, v6
	v_lshlrev_b32_e32 v6, 16, v7
	v_and_b32_e32 v7, 0xffff0000, v7
	s_waitcnt vmcnt(0)
	v_pk_mul_f32 v[2:3], v[10:11], v[2:3]
	v_pk_mul_f32 v[4:5], v[14:15], v[4:5]
	v_pk_mul_f32 v[2:3], v[2:3], v[16:17]
	v_pk_mul_f32 v[4:5], v[4:5], v[6:7]
	v_cvt_pk_bf16_f32 v2, v2, v3
	v_cvt_pk_bf16_f32 v3, v4, v5
	global_store_dwordx2 v[12:13], v[2:3], off offset:32
	global_load_dwordx2 v[4:5], v[0:1], off offset:112
	s_nop 0
	global_load_dwordx4 v[0:3], v192, s[4:5] offset:224
	v_pk_mul_f32 v[6:7], v[8:9], v[28:29] op_sel_hi:[1,0]
	v_pk_mul_f32 v[8:9], v[30:31], v[28:29] op_sel_hi:[1,0]
	s_mov_b64 s[4:5], 0
	s_waitcnt vmcnt(1)
	v_lshlrev_b32_e32 v10, 16, v4
	v_and_b32_e32 v11, 0xffff0000, v4
	v_lshlrev_b32_e32 v4, 16, v5
	v_and_b32_e32 v5, 0xffff0000, v5
	s_waitcnt vmcnt(0)
	v_pk_mul_f32 v[0:1], v[6:7], v[0:1]
	v_pk_mul_f32 v[2:3], v[8:9], v[2:3]
	v_pk_mul_f32 v[0:1], v[0:1], v[10:11]
	v_pk_mul_f32 v[2:3], v[2:3], v[4:5]
	v_cvt_pk_bf16_f32 v0, v0, v1
	v_cvt_pk_bf16_f32 v1, v2, v3
	global_store_dwordx2 v[12:13], v[0:1], off offset:48
	s_branch .LBB0_71
